# QKV GEMM tile order: spread the tiles with f32 window-output epilogues evenly over workgroups (on top of S5 XCD remap + global stores)
# speedup vs baseline: 1.0510x; 1.0002x over previous
; DI bool unit_next(int i, int G, int c, int nM, int nN, int& pm, int& pn) {
;     const int nwg = nM * nN; const long L = (long)i * G + c; if (L >= nwg) return false;
;     int wgid = (int)L; { const int q = nwg / NXCD, r = nwg % NXCD, xcd = wgid % NXCD, off = wgid / NXCD; wgid = (xcd < r ? xcd * (q + 1) : r * (q + 1) + (xcd - r) * q) + off; }
;     const int nig = WGM * nN, gid = wgid / nig, fm = gid * WGM, gsz = (nM - fm) < WGM ? (nM - fm) : WGM;
;     pm = fm + ((wgid % nig) % gsz); pn = (wgid % nig) / gsz; return true;
; }
;     DI bool get(int i, const bf16_t*& a, const bf16_t*& b, EpiT& e) const { int pm, pn; if (!unit_next(i, G, c, nM, nN, pm, pn)) return false;
;         a = A + (size_t)pm * astep + (size_t)pn * acolstep; b = Bt + (size_t)pn * bstep; e = proto; e.set(pm, pn); return true; }
.LBB0_1236:
	s_cmp_lt_i32 s74, 12
	s_cselect_b64 s[0:1], -1, 0
	s_cmp_gt_i32 s75, 11
	s_cselect_b64 s[2:3], -1, 0
	s_and_b64 s[0:1], s[0:1], s[2:3]
	s_andn2_b64 vcc, exec, s[0:1]
	s_cbranch_vccnz .LBB0_1388
	s_waitcnt lgkmcnt(0)
	s_add_u32 s20, s90, 0x4400000
	s_addc_u32 s21, s91, 0
	v_readlane_b32 s0, v254, 0
	s_add_u32 s4, s90, 0x700000
	v_readlane_b32 s1, v254, 1
	s_addc_u32 s5, s91, 0
	s_load_dwordx2 s[16:17], s[0:1], 0xd0
	s_add_u32 s18, s90, 0x14800000
	s_addc_u32 s19, s91, 0
	s_cmpk_lt_i32 s84, 0x600
	s_cselect_b64 s[6:7], -1, 0
	s_cmpk_gt_i32 s84, 0x5ff
	v_mbcnt_lo_u32_b32 v144, -1, 0
	v_mbcnt_hi_u32_b32 v144, -1, v144
	v_mbcnt_lo_u32_b32 v0, -1, 0
	v_mbcnt_hi_u32_b32 v0, -1, v0
	s_cbranch_scc1 .LBB0_1239
	s_ashr_i32 s0, s84, 31
	s_lshr_b32 s0, s0, 29
	s_add_i32 s0, s84, s0
	s_ashr_i32 s1, s0, 3
	s_and_b32 s0, s0, -8
	s_sub_i32 s0, s84, s0
	s_cmp_lt_i32 s0, 0
	s_movk_i32 s2, 0xc1
	s_cselect_b32 s2, s2, 0xc0
	s_mul_i32 s0, s0, s2
	s_add_i32 s0, s0, s1
	s_mul_hi_i32 s1, s0, 0x2aaaaaab
	s_lshr_b32 s2, s1, 31
	s_ashr_i32 s1, s1, 4
	s_add_i32 s1, s1, s2
	s_mul_i32 s2, s1, 0x60
	s_sub_i32 s0, s0, s2
	s_bfe_i32 s2, s0, 0x80000
	s_bfe_u32 s2, s2, 0x3000c
	s_add_i32 s3, s0, s2
	s_bfe_i32 s2, s3, 0x80000
	s_and_b32 s3, s3, 0xf8
	s_sub_i32 s0, s0, s3
	s_lshl_b32 s1, s1, 3
	s_sext_i32_i8 s0, s0
	s_add_i32 s10, s1, s0
	s_sext_i32_i16 s2, s2
	s_ashr_i32 s11, s10, 31
	s_lshr_b32 s2, s2, 3
	s_lshr_b32 s3, s2, 2
	s_lshl_b32 s3, s3, 1
	s_add_i32 s0, s0, s3
	s_lshr_b32 s3, s1, 1
	s_and_b32 s3, s3, 4
	s_add_i32 s0, s0, s3
	s_and_b32 s0, s0, 7
	s_lshl_b32 s0, s0, 2
	s_bfe_u32 s3, s1, 0x20003
	s_or_b32 s0, s0, s3
	s_and_b32 s1, s1, -32
	s_or_b32 s1, s1, s0
	s_mov_b32 s10, s1
	s_mov_b32 s11, 0
	s_lshl_b64 s[0:1], s[10:11], 19
	s_add_u32 s0, s20, s0
	s_addc_u32 s1, s21, s1
	s_bfe_i64 s[8:9], s[2:3], 0x100000
	s_lshl_b64 s[8:9], s[8:9], 19
	s_add_u32 s8, s4, s8
	s_addc_u32 s9, s5, s9
	s_lshl_b32 s46, s10, 8
	s_lshl_b32 s14, s2, 8
	s_andn2_b64 vcc, exec, s[6:7]
	s_cbranch_vccz .LBB0_1240
	s_branch .LBB0_1383

; DI bool unit_next(int i, int G, int c, int nM, int nN, int& pm, int& pn) {
;     const int nwg = nM * nN; const long L = (long)i * G + c; if (L >= nwg) return false;
;     int wgid = (int)L; { const int q = nwg / NXCD, r = nwg % NXCD, xcd = wgid % NXCD, off = wgid / NXCD; wgid = (xcd < r ? xcd * (q + 1) : r * (q + 1) + (xcd - r) * q) + off; }
;     const int nig = WGM * nN, gid = wgid / nig, fm = gid * WGM, gsz = (nM - fm) < WGM ? (nM - fm) : WGM;
;     pm = fm + ((wgid % nig) % gsz); pn = (wgid % nig) / gsz; return true;
; }
;     DI bool get(int i, const bf16_t*& a, const bf16_t*& b, EpiT& e) const { int pm, pn; if (!unit_next(i, G, c, nM, nN, pm, pn)) return false;
;         a = A + (size_t)pm * astep + (size_t)pn * acolstep; b = Bt + (size_t)pn * bstep; e = proto; e.set(pm, pn); return true; }
.LBB0_1245:
	s_add_i32 s42, s42, 1
	s_mul_i32 s6, s42, s45
	s_mul_hi_u32 s7, s42, s47
	s_add_i32 s7, s7, s6
	s_mul_i32 s6, s42, s47
	s_add_u32 s10, s6, s84
	s_addc_u32 s11, s7, s48
	v_cmp_gt_i64_e32 vcc, s[10:11], v[130:131]
	v_cmp_lt_i64_e64 s[6:7], s[10:11], v[128:129]
	s_cbranch_vccnz .LBB0_1247
	s_ashr_i32 s11, s10, 31
	s_lshr_b32 s11, s11, 29
	s_add_i32 s11, s10, s11
	s_ashr_i32 s12, s11, 3
	s_and_b32 s11, s11, -8
	s_sub_i32 s10, s10, s11
	s_cmp_lt_i32 s10, 0
	s_cselect_b32 s11, s49, 0xc0
	s_mul_i32 s10, s10, s11
	s_add_i32 s10, s10, s12
	s_mul_hi_i32 s11, s10, 0x2aaaaaab
	s_lshr_b32 s12, s11, 31
	s_ashr_i32 s11, s11, 4
	s_add_i32 s11, s11, s12
	s_lshl_b32 s12, s11, 3
	s_sub_i32 s13, 0x80, s12
	s_min_i32 s13, s13, 8
	s_abs_i32 s15, s13
	v_cvt_f32_u32_e32 v0, s15
	s_sub_i32 s27, 0, s15
	s_mulk_i32 s11, 0x60
	s_sub_i32 s11, s10, s11
	v_rcp_iflag_f32_e32 v0, v0
	s_abs_i32 s10, s11
	s_xor_b32 s26, s11, s13
	s_ashr_i32 s26, s26, 31
	v_mul_f32_e32 v0, 0x4f7ffffe, v0
	v_cvt_u32_f32_e32 v0, v0
	s_nop 0
	v_readfirstlane_b32 s28, v0
	s_mul_i32 s27, s27, s28
	s_mul_hi_u32 s27, s28, s27
	s_add_i32 s28, s28, s27
	s_mul_hi_u32 s27, s10, s28
	s_mul_i32 s28, s27, s15
	s_sub_i32 s10, s10, s28
	s_add_i32 s29, s27, 1
	s_sub_i32 s28, s10, s15
	s_cmp_ge_u32 s10, s15
	s_cselect_b32 s27, s29, s27
	s_cselect_b32 s10, s28, s10
	s_add_i32 s28, s27, 1
	s_cmp_ge_u32 s10, s15
	s_cselect_b32 s10, s28, s27
	s_xor_b32 s10, s10, s26
	s_sub_i32 s10, s10, s26
	s_mul_i32 s13, s10, s13
	s_sub_i32 s11, s11, s13
	s_lshr_b32 s13, s10, 2
	s_lshl_b32 s13, s13, 1
	s_add_i32 s11, s11, s13
	s_lshr_b32 s13, s12, 1
	s_and_b32 s13, s13, 4
	s_add_i32 s11, s11, s13
	s_and_b32 s11, s11, 7
	s_lshl_b32 s11, s11, 2
	s_bfe_u32 s13, s12, 0x20003
	s_or_b32 s11, s11, s13
	s_and_b32 s12, s12, -32
	s_or_b32 s12, s12, s11
	s_ashr_i32 s13, s12, 31
	s_lshl_b64 s[26:27], s[12:13], 19
	s_add_u32 s26, s20, s26
	s_addc_u32 s27, s21, s27
	s_ashr_i32 s11, s10, 31
	s_lshl_b64 s[28:29], s[10:11], 19
	s_add_u32 s28, s4, s28
	s_addc_u32 s29, s5, s29
	s_lshl_b32 s58, s12, 8
	s_lshl_b32 s57, s10, 8
